# retention chunk items: hipcc read->wait->MFMA ladders replaced by 9-deep LDS fragment ring with counted waits (same MFMAs and accumulation order)
# speedup vs baseline: 1.0046x; 1.0046x over previous
.LBB0_340:
	v_log_f32_e32 v85, v85
	v_add_u32_e32 v113, s11, v3
	v_add_u32_e32 v115, s33, v3
	s_mul_i32 s39, s40, 0x840
	v_sub_f32_e32 v111, v85, v84
	ds_read_b128 v[220:223], v113 offset:16384
	ds_read_b128 v[224:227], v115
	ds_read_b128 v[228:231], v115 offset:2048
	ds_read_b128 v[232:235], v113 offset:17408
	ds_read_b128 v[236:239], v115 offset:1024
	ds_read_b128 v[240:243], v115 offset:3072
	ds_read_b128 v[244:247], v113 offset:24576
	ds_read_b128 v[248:251], v115 offset:8192
	ds_read_b128 v[212:215], v115 offset:10240
	s_sub_i32 s39, s18, s39
	s_lshr_b32 s41, s40, 3
	s_mul_hi_u32 s40, s41, 0x840
	s_mulk_i32 s41, 0x840
	s_ashr_i32 s42, s39, 31
	s_add_u32 s60, s39, s41
	s_addc_u32 s61, s42, s40
	s_lshl_b32 s52, s23, 9
	s_mov_b64 s[40:41], 0x40000
	s_addk_i32 s22, 0x200
	s_add_i32 s19, s19, 8
	v_lshl_add_u64 v[108:109], v[108:109], 0, s[40:41]
	s_addk_i32 s18, 0x200
	s_waitcnt lgkmcnt(7)
	v_mfma_f32_16x16x32_bf16 v[88:91], v[220:223], v[224:227], 0
	s_waitcnt lgkmcnt(6)
	v_mfma_f32_16x16x32_bf16 v[84:87], v[220:223], v[228:231], 0
	ds_read_b128 v[220:223], v113 offset:25600
	ds_read_b128 v[224:227], v115 offset:9216
	ds_read_b128 v[228:231], v115 offset:11264
	v_add_u32_e32 v113, 0, v3
	v_add_u32_e32 v115, 0x10000, v113
	s_waitcnt lgkmcnt(7)
	v_mfma_f32_16x16x32_bf16 v[88:91], v[232:235], v[236:239], v[88:91]
	s_waitcnt lgkmcnt(6)
	v_mfma_f32_16x16x32_bf16 v[84:87], v[232:235], v[240:243], v[84:87]
	s_waitcnt lgkmcnt(4)
	v_mfma_f32_16x16x32_bf16 v[88:91], v[244:247], v[248:251], v[88:91]
	s_waitcnt lgkmcnt(3)
	v_mfma_f32_16x16x32_bf16 v[84:87], v[244:247], v[212:215], v[84:87]
	s_waitcnt lgkmcnt(1)
	v_mfma_f32_16x16x32_bf16 v[88:91], v[220:223], v[224:227], v[88:91]
	s_waitcnt lgkmcnt(0)
	v_mfma_f32_16x16x32_bf16 v[84:87], v[220:223], v[228:231], v[84:87]
	v_mul_f32_e32 v92, v128, v111
	v_mul_f32_e32 v93, v129, v111
	v_exp_f32_e32 v92, v92
	v_exp_f32_e32 v93, v93
	s_nop 1
	v_pk_mul_f32 v[88:89], v[92:93], v[88:89]
	v_mul_f32_e32 v92, v130, v111
	v_mul_f32_e32 v93, v131, v111
	v_exp_f32_e32 v92, v92
	v_exp_f32_e32 v93, v93
	v_cvt_pk_bf16_f32 v88, v88, v89
	v_pk_mul_f32 v[90:91], v[92:93], v[90:91]
	s_nop 0
	v_cvt_pk_bf16_f32 v89, v90, v91
	v_mul_f32_e32 v90, v132, v111
	v_mul_f32_e32 v91, v133, v111
	v_exp_f32_e32 v90, v90
	v_exp_f32_e32 v91, v91
	s_nop 0
	v_pk_mul_f32 v[84:85], v[90:91], v[84:85]
	v_mul_f32_e32 v90, v134, v111
	v_mul_f32_e32 v91, v135, v111
	v_exp_f32_e32 v90, v90
	v_exp_f32_e32 v91, v91
	v_cvt_pk_bf16_f32 v84, v84, v85
	v_pk_mul_f32 v[86:87], v[90:91], v[86:87]
	s_nop 0
	v_cvt_pk_bf16_f32 v85, v86, v87
	ds_write2st64_b64 v188, v[88:89], v[84:85] offset1:4
	v_add_u32_e32 v84, s38, v3
	s_waitcnt lgkmcnt(0)
	s_barrier
	ds_read_b128 v[96:99], v84 offset:49152
	ds_read_b128 v[116:119], v84 offset:50176
	ds_read_b128 v[220:223], v115
	ds_read_b128 v[224:227], v115 offset:2048
	ds_read_b128 v[228:231], v115 offset:4096
	ds_read_b128 v[232:235], v115 offset:6144
	ds_read_b128 v[236:239], v115 offset:1024
	ds_read_b128 v[240:243], v115 offset:3072
	ds_read_b128 v[244:247], v115 offset:5120
	ds_read_b128 v[248:251], v115 offset:7168
	ds_read_b128 v[212:215], v113
	s_waitcnt lgkmcnt(8)
	v_mfma_f32_16x16x32_bf16 v[84:87], v[220:223], v[96:99], 0
	ds_read_b128 v[220:223], v113 offset:2048
	s_waitcnt lgkmcnt(8)
	v_mfma_f32_16x16x32_bf16 v[88:91], v[224:227], v[96:99], 0
	ds_read_b128 v[224:227], v113 offset:4096
	s_waitcnt lgkmcnt(8)
	v_mfma_f32_16x16x32_bf16 v[92:95], v[228:231], v[96:99], 0
	ds_read_b128 v[228:231], v113 offset:6144
	s_waitcnt lgkmcnt(8)
	v_mfma_f32_16x16x32_bf16 v[96:99], v[232:235], v[96:99], 0
	ds_read_b128 v[232:235], v113 offset:1024
	s_waitcnt lgkmcnt(8)
	v_mfma_f32_16x16x32_bf16 v[84:87], v[236:239], v[116:119], v[84:87]
	ds_read_b128 v[236:239], v113 offset:3072
	s_waitcnt lgkmcnt(8)
	v_mfma_f32_16x16x32_bf16 v[88:91], v[240:243], v[116:119], v[88:91]
	ds_read_b128 v[240:243], v113 offset:5120
	s_waitcnt lgkmcnt(8)
	v_mfma_f32_16x16x32_bf16 v[92:95], v[244:247], v[116:119], v[92:95]
	ds_read_b128 v[244:247], v113 offset:7168
	s_waitcnt lgkmcnt(8)
	v_mfma_f32_16x16x32_bf16 v[96:99], v[248:251], v[116:119], v[96:99]
	ds_read_b128 v[248:251], v113 offset:8192
	s_waitcnt lgkmcnt(8)
	v_mfma_f32_16x16x32_bf16 v[116:119], v[212:215], v[80:83], 0
	ds_read_b128 v[212:215], v113 offset:10240
	s_waitcnt lgkmcnt(8)
	v_mfma_f32_16x16x32_bf16 v[190:193], v[220:223], v[80:83], 0
	ds_read_b128 v[220:223], v113 offset:12288
	s_waitcnt lgkmcnt(8)
	v_mfma_f32_16x16x32_bf16 v[208:211], v[224:227], v[80:83], 0
	ds_read_b128 v[224:227], v113 offset:14336
	s_waitcnt lgkmcnt(8)
	v_mfma_f32_16x16x32_bf16 v[80:83], v[228:231], v[80:83], 0
	ds_read_b128 v[228:231], v113 offset:9216
	s_waitcnt lgkmcnt(8)
	v_mfma_f32_16x16x32_bf16 v[116:119], v[232:235], v[76:79], v[116:119]
	ds_read_b128 v[232:235], v113 offset:11264
	s_waitcnt lgkmcnt(8)
	v_mfma_f32_16x16x32_bf16 v[190:193], v[236:239], v[76:79], v[190:193]
	ds_read_b128 v[236:239], v113 offset:13312
	s_waitcnt lgkmcnt(8)
	v_mfma_f32_16x16x32_bf16 v[208:211], v[240:243], v[76:79], v[208:211]
	ds_read_b128 v[240:243], v113 offset:15360
	s_waitcnt lgkmcnt(8)
	v_mfma_f32_16x16x32_bf16 v[76:79], v[244:247], v[76:79], v[80:83]
	s_waitcnt lgkmcnt(7)
	v_mfma_f32_16x16x32_bf16 v[80:83], v[248:251], v[72:75], v[116:119]
	s_waitcnt lgkmcnt(6)
	v_mfma_f32_16x16x32_bf16 v[116:119], v[212:215], v[72:75], v[190:193]
	s_waitcnt lgkmcnt(5)
	v_mfma_f32_16x16x32_bf16 v[190:193], v[220:223], v[72:75], v[208:211]
	s_waitcnt lgkmcnt(4)
	v_mfma_f32_16x16x32_bf16 v[72:75], v[224:227], v[72:75], v[76:79]
	s_waitcnt lgkmcnt(3)
	v_mfma_f32_16x16x32_bf16 v[76:79], v[228:231], v[68:71], v[80:83]
	s_waitcnt lgkmcnt(2)
	v_mfma_f32_16x16x32_bf16 v[80:83], v[232:235], v[68:71], v[116:119]
	s_waitcnt lgkmcnt(1)
	v_mfma_f32_16x16x32_bf16 v[116:119], v[236:239], v[68:71], v[190:193]
	s_waitcnt lgkmcnt(0)
	v_mfma_f32_16x16x32_bf16 v[68:71], v[240:243], v[68:71], v[72:75]
	s_nop 2
	v_mul_f32_e32 v72, v111, v136
	v_exp_f32_e32 v72, v72
	v_mul_f32_e32 v74, v111, v138
	v_mul_f32_e32 v75, v111, v139
	v_exp_f32_e32 v74, v74
	v_fma_f32 v72, v72, v76, v84
	v_mul_f32_e32 v76, v111, v141
	v_exp_f32_e32 v76, v76
	v_exp_f32_e32 v75, v75
	v_fma_f32 v74, v74, v78, v86
	v_mul_f32_e32 v78, v111, v143
	v_fma_f32 v76, v76, v81, v89
	v_mul_f32_e32 v81, v111, v147
	v_exp_f32_e32 v81, v81
	v_fmac_f32_e32 v87, v75, v79
	v_mul_f32_e32 v75, v111, v140
	v_mul_f32_e32 v73, v111, v137
	v_fmac_f32_e32 v95, v81, v119
	v_mul_f32_e32 v81, v111, v148
	v_exp_f32_e32 v81, v81
	v_exp_f32_e32 v75, v75
	v_exp_f32_e32 v78, v78
	v_exp_f32_e32 v73, v73
	v_fma_f32 v68, v81, v68, v96
	v_mul_f32_e32 v81, v111, v149
	v_exp_f32_e32 v81, v81
	v_fma_f32 v75, v75, v80, v88
	v_fmac_f32_e32 v91, v78, v83
	v_mul_f32_e32 v78, v111, v144
	v_fma_f32 v69, v81, v69, v97
	v_mul_f32_e32 v81, v111, v162
	v_exp_f32_e32 v81, v81
	v_mul_f32_e32 v79, v111, v145
	v_mul_f32_e32 v80, v111, v146
	v_fma_f32 v73, v73, v77, v85
	v_mul_f32_e32 v77, v111, v142
	v_exp_f32_e32 v78, v78
	v_exp_f32_e32 v79, v79
	v_exp_f32_e32 v80, v80
	v_fma_f32 v70, v81, v70, v98
	v_mul_f32_e32 v81, v111, v163
	v_exp_f32_e32 v77, v77
	v_exp_f32_e32 v81, v81
	v_fma_f32 v78, v78, v116, v92
	v_fma_f32 v79, v79, v117, v93
	v_fma_f32 v80, v80, v118, v94
	v_fma_f32 v77, v77, v82, v90
	v_fmac_f32_e32 v99, v81, v71
	ds_write_b32 v103, v72
	ds_write_b32 v164, v73
	ds_write_b32 v165, v74
	ds_write_b32 v166, v87
	ds_write_b32 v167, v75
	ds_write_b32 v168, v76
	ds_write_b32 v169, v77
	ds_write_b32 v170, v91
	ds_write_b32 v171, v78
	ds_write_b32 v172, v79
	ds_write_b32 v173, v80
	ds_write_b32 v174, v95
	ds_write_b32 v127, v68
	ds_write_b32 v175, v69
	ds_write_b32 v176, v70
	ds_write_b32 v177, v99
	s_waitcnt lgkmcnt(0)
	s_barrier
	ds_read_b128 v[82:85], v120
	ds_read_b128 v[78:81], v121
	ds_read_b128 v[72:75], v122
	ds_read_b128 v[68:71], v123
	v_lshl_add_u64 v[90:91], v[106:107], 0, s[52:53]
	v_lshlrev_b32_e32 v190, 16, v64
	s_waitcnt lgkmcnt(2)
	v_pk_add_f32 v[86:87], v[82:83], v[78:79]
	v_pk_add_f32 v[76:77], v[84:85], v[80:81]
	s_waitcnt lgkmcnt(1)
	v_pk_add_f32 v[86:87], v[86:87], v[72:73]
	v_pk_add_f32 v[76:77], v[76:77], v[74:75]
	s_waitcnt lgkmcnt(0)
	v_pk_add_f32 v[86:87], v[86:87], v[68:69]
	v_pk_add_f32 v[76:77], v[76:77], v[70:71]
	v_add_f32_e32 v86, v86, v87
	v_add_f32_e32 v76, v76, v86
	v_add_f32_e32 v76, v77, v76
	ds_bpermute_b32 v77, v124, v76
	v_and_b32_e32 v191, 0xffff0000, v64
	v_mul_f32_e32 v64, 0xbfb8aa3b, v190
	v_exp_f32_e32 v64, v64
	v_lshl_add_u64 v[94:95], s[60:61], 0, v[100:101]
	s_waitcnt lgkmcnt(0)
	v_add_f32_e32 v76, v76, v77
	ds_bpermute_b32 v77, v125, v76
	v_add_f32_e32 v64, 1.0, v64
	v_rcp_f32_e32 v192, v64
	v_mul_f32_e32 v64, 0xbfb8aa3b, v191
	v_exp_f32_e32 v64, v64
	s_waitcnt lgkmcnt(0)
	v_add_f32_e32 v76, v76, v77
	ds_bpermute_b32 v77, v126, v76
	s_lshl_b32 s52, s23, 8
	v_add_f32_e32 v64, 1.0, v64
	v_rcp_f32_e32 v193, v64
	s_waitcnt lgkmcnt(0)
	v_add_f32_e32 v76, v76, v77
	v_fmamk_f32 v79, v76, 0xbc000000, v79
	v_fmac_f32_e32 v78, 0xbc000000, v76
	v_fmamk_f32 v119, v76, 0xbc000000, v83
	v_fmamk_f32 v118, v76, 0xbc000000, v82
	v_fmamk_f32 v117, v76, 0xbc000000, v81
	v_fmamk_f32 v116, v76, 0xbc000000, v80
	v_fmamk_f32 v97, v76, 0xbc000000, v69
	v_fmamk_f32 v96, v76, 0xbc000000, v68
	v_pk_mul_f32 v[68:69], v[78:79], v[78:79]
	v_fmamk_f32 v85, v76, 0xbc000000, v85
	v_fmac_f32_e32 v84, 0xbc000000, v76
	v_fmamk_f32 v99, v76, 0xbc000000, v75
	v_fmamk_f32 v98, v76, 0xbc000000, v74
	v_fmamk_f32 v73, v76, 0xbc000000, v73
	v_fmac_f32_e32 v72, 0xbc000000, v76
	v_pk_mul_f32 v[74:75], v[116:117], v[116:117]
	v_pk_fma_f32 v[68:69], v[118:119], v[118:119], v[68:69]
	v_pk_fma_f32 v[74:75], v[84:85], v[84:85], v[74:75]
	v_pk_fma_f32 v[68:69], v[72:73], v[72:73], v[68:69]
	v_fmamk_f32 v71, v76, 0xbc000000, v71
	v_fmac_f32_e32 v70, 0xbc000000, v76
	v_pk_fma_f32 v[74:75], v[98:99], v[98:99], v[74:75]
	v_pk_fma_f32 v[68:69], v[96:97], v[96:97], v[68:69]
	v_pk_fma_f32 v[74:75], v[70:71], v[70:71], v[74:75]
	v_add_f32_e32 v68, v68, v69
	v_add_f32_e32 v68, v74, v68
	v_add_f32_e32 v68, v75, v68
	global_load_dwordx4 v[74:77], v[90:91], off offset:48
	global_load_dwordx4 v[80:83], v[90:91], off offset:32
	global_load_dwordx4 v[86:89], v[90:91], off offset:16
	s_nop 0
	global_load_dwordx4 v[90:93], v[90:91], off
	ds_bpermute_b32 v69, v124, v68
	s_waitcnt lgkmcnt(0)
	v_add_f32_e32 v68, v68, v69
	ds_bpermute_b32 v69, v125, v68
	s_waitcnt lgkmcnt(0)
	v_add_f32_e32 v68, v68, v69
	ds_bpermute_b32 v69, v126, v68
	s_waitcnt lgkmcnt(0)
	v_add_f32_e32 v68, v68, v69
	v_fmamk_f32 v68, v68, 0x3c000000, v180
	v_cmp_gt_f32_e32 vcc, s7, v68
	v_mul_f32_e32 v69, 0x4b800000, v68
	s_nop 0
	v_cndmask_b32_e32 v68, v68, v69, vcc
	v_rsq_f32_e32 v68, v68
	s_nop 0
	v_mul_f32_e32 v69, 0x45800000, v68
	v_cndmask_b32_e32 v68, v68, v69, vcc
	v_pk_mul_f32 v[118:119], v[118:119], v[68:69] op_sel_hi:[1,0]
	v_pk_mul_f32 v[84:85], v[84:85], v[68:69] op_sel_hi:[1,0]
	v_pk_mul_f32 v[78:79], v[78:79], v[68:69] op_sel_hi:[1,0]
	v_pk_mul_f32 v[72:73], v[72:73], v[68:69] op_sel_hi:[1,0]
	s_andn2_b64 vcc, exec, s[36:37]
	s_waitcnt vmcnt(2)
	v_pk_mul_f32 v[72:73], v[80:81], v[72:73]
	s_waitcnt vmcnt(1)
	v_pk_mul_f32 v[78:79], v[86:87], v[78:79]
	s_waitcnt vmcnt(0)
	v_pk_mul_f32 v[90:91], v[90:91], v[118:119]
	v_pk_mul_f32 v[118:119], v[192:193], v[190:191]
	v_pk_mul_f32 v[84:85], v[92:93], v[84:85]
	v_pk_mul_f32 v[90:91], v[118:119], v[90:91]
	v_pk_mul_f32 v[86:87], v[116:117], v[68:69] op_sel_hi:[1,0]
	v_cvt_pk_bf16_f32 v64, v90, v91
	v_lshlrev_b32_e32 v90, 16, v65
	v_and_b32_e32 v91, 0xffff0000, v65
	v_mul_f32_e32 v65, 0xbfb8aa3b, v90
	v_exp_f32_e32 v65, v65
	v_pk_mul_f32 v[86:87], v[88:89], v[86:87]
	v_pk_mul_f32 v[80:81], v[98:99], v[68:69] op_sel_hi:[1,0]
	v_add_f32_e32 v65, 1.0, v65
	v_rcp_f32_e32 v118, v65
	v_mul_f32_e32 v65, 0xbfb8aa3b, v91
	v_exp_f32_e32 v65, v65
	v_pk_mul_f32 v[80:81], v[82:83], v[80:81]
	v_add_f32_e32 v65, 1.0, v65
	v_rcp_f32_e32 v119, v65
	s_nop 0
	v_pk_mul_f32 v[90:91], v[118:119], v[90:91]
	s_nop 0
	v_pk_mul_f32 v[84:85], v[90:91], v[84:85]
	s_nop 0
	v_cvt_pk_bf16_f32 v65, v84, v85
	v_lshlrev_b32_e32 v84, 16, v66
	v_and_b32_e32 v85, 0xffff0000, v66
	v_mul_f32_e32 v66, 0xbfb8aa3b, v84
	v_exp_f32_e32 v66, v66
	s_nop 0
	v_add_f32_e32 v66, 1.0, v66
	v_rcp_f32_e32 v90, v66
	v_mul_f32_e32 v66, 0xbfb8aa3b, v85
	v_exp_f32_e32 v66, v66
	s_nop 0
	v_add_f32_e32 v66, 1.0, v66
	v_rcp_f32_e32 v91, v66
	s_nop 0
	v_pk_mul_f32 v[84:85], v[90:91], v[84:85]
	s_nop 0
	v_pk_mul_f32 v[78:79], v[84:85], v[78:79]
	s_nop 0
	v_cvt_pk_bf16_f32 v66, v78, v79
	v_lshlrev_b32_e32 v78, 16, v67
	v_and_b32_e32 v79, 0xffff0000, v67
	v_mul_f32_e32 v67, 0xbfb8aa3b, v78
	v_exp_f32_e32 v67, v67
	s_nop 0
	v_add_f32_e32 v67, 1.0, v67
	v_rcp_f32_e32 v84, v67
	v_mul_f32_e32 v67, 0xbfb8aa3b, v79
	v_exp_f32_e32 v67, v67
	s_nop 0
	v_add_f32_e32 v67, 1.0, v67
	v_rcp_f32_e32 v85, v67
	s_nop 0
	v_pk_mul_f32 v[78:79], v[84:85], v[78:79]
	s_nop 0
	v_pk_mul_f32 v[78:79], v[78:79], v[86:87]
	s_nop 0
	v_cvt_pk_bf16_f32 v67, v78, v79
	v_lshlrev_b32_e32 v78, 16, v36
	v_and_b32_e32 v79, 0xffff0000, v36
	v_mul_f32_e32 v36, 0xbfb8aa3b, v78
	v_exp_f32_e32 v36, v36
	s_nop 0
	v_add_f32_e32 v36, 1.0, v36
	v_rcp_f32_e32 v84, v36
	v_mul_f32_e32 v36, 0xbfb8aa3b, v79
	v_exp_f32_e32 v36, v36
	s_nop 0
	v_add_f32_e32 v36, 1.0, v36
	v_rcp_f32_e32 v85, v36
	s_nop 0
	v_pk_mul_f32 v[78:79], v[84:85], v[78:79]
	s_nop 0
	v_pk_mul_f32 v[72:73], v[78:79], v[72:73]
	s_nop 0
	v_cvt_pk_bf16_f32 v36, v72, v73
	v_lshlrev_b32_e32 v72, 16, v37
	v_and_b32_e32 v73, 0xffff0000, v37
	v_mul_f32_e32 v37, 0xbfb8aa3b, v72
	v_exp_f32_e32 v37, v37
	s_nop 0
	v_add_f32_e32 v37, 1.0, v37
	v_rcp_f32_e32 v78, v37
	v_mul_f32_e32 v37, 0xbfb8aa3b, v73
	v_exp_f32_e32 v37, v37
	s_nop 0
	v_add_f32_e32 v37, 1.0, v37
	v_rcp_f32_e32 v79, v37
	s_nop 0
	v_pk_mul_f32 v[72:73], v[78:79], v[72:73]
	s_nop 0
	v_pk_mul_f32 v[72:73], v[72:73], v[80:81]
	v_pk_mul_f32 v[80:81], v[96:97], v[68:69] op_sel_hi:[1,0]
	v_cvt_pk_bf16_f32 v37, v72, v73
	v_lshlrev_b32_e32 v72, 16, v38
	v_and_b32_e32 v73, 0xffff0000, v38
	v_mul_f32_e32 v38, 0xbfb8aa3b, v72
	v_exp_f32_e32 v38, v38
	v_pk_mul_f32 v[74:75], v[74:75], v[80:81]
	v_pk_mul_f32 v[68:69], v[70:71], v[68:69] op_sel_hi:[1,0]
	v_mov_b64_e32 v[82:83], v[54:55]
	v_add_f32_e32 v38, 1.0, v38
	v_rcp_f32_e32 v78, v38
	v_mul_f32_e32 v38, 0xbfb8aa3b, v73
	v_exp_f32_e32 v38, v38
	v_pk_mul_f32 v[68:69], v[76:77], v[68:69]
	v_mov_b64_e32 v[80:81], v[52:53]
	v_add_f32_e32 v38, 1.0, v38
	v_rcp_f32_e32 v79, v38
	s_nop 0
	v_pk_mul_f32 v[72:73], v[78:79], v[72:73]
	s_nop 0
	v_pk_mul_f32 v[72:73], v[72:73], v[74:75]
	v_mov_b64_e32 v[78:79], v[50:51]
	v_cvt_pk_bf16_f32 v38, v72, v73
	v_lshlrev_b32_e32 v72, 16, v39
	v_and_b32_e32 v73, 0xffff0000, v39
	v_mul_f32_e32 v39, 0xbfb8aa3b, v72
	v_exp_f32_e32 v39, v39
	v_mov_b64_e32 v[76:77], v[48:49]
	v_add_f32_e32 v39, 1.0, v39
	v_rcp_f32_e32 v74, v39
	v_mul_f32_e32 v39, 0xbfb8aa3b, v73
	v_exp_f32_e32 v39, v39
	s_nop 0
	v_add_f32_e32 v39, 1.0, v39
	v_rcp_f32_e32 v75, v39
	s_nop 0
	v_pk_mul_f32 v[70:71], v[74:75], v[72:73]
	s_nop 0
	v_pk_mul_f32 v[68:69], v[70:71], v[68:69]
	v_mov_b64_e32 v[74:75], v[46:47]
	v_cvt_pk_bf16_f32 v39, v68, v69
	v_lshlrev_b64 v[68:69], 12, v[94:95]
	v_lshl_add_u64 v[68:69], v[4:5], 0, v[68:69]
	v_lshl_add_u64 v[68:69], v[68:69], 0, s[52:53]
	v_lshl_add_u64 v[68:69], v[68:69], 0, v[0:1]
	global_store_dwordx4 v[68:69], v[64:67], off
	global_store_dwordx4 v[68:69], v[36:39], off offset:16
	v_mov_b64_e32 v[70:71], v[42:43]
	v_mov_b64_e32 v[66:67], v[62:63]
	v_mov_b64_e32 v[36:37], v[56:57]
	v_mov_b64_e32 v[72:73], v[44:45]
	v_mov_b64_e32 v[68:69], v[40:41]
	v_mov_b64_e32 v[64:65], v[60:61]
	v_mov_b64_e32 v[38:39], v[58:59]
	s_cbranch_vccz .LBB0_343
